# v33 + gla1 and gla3 item tails: adjacent-block dwordx2 output stores merged pairwise into dwordx4 stores with v_permlane16_swap (half the store instructions)
# baseline (speedup 1.0000x reference)
; #define LAS __attribute__((address_space(3)))
; __device__ __forceinline__ unsigned cvt_pk_bf16(float lo, float hi) { const f32x2 f = {lo, hi}; const bf16n2 v = __builtin_convertvector(f, bf16n2); return __builtin_bit_cast(unsigned, v); }
; __device__ __forceinline__ f32x4 mfma16(bf16x8 colfrag, bf16x8 rowfrag, f32x4 acc) { return __builtin_amdgcn_mfma_f32_16x16x32_bf16(colfrag, rowfrag, acc, 0, 0, 0); }
; __device__ __forceinline__ float shx(float v, int lane, int o) { return __int_as_float(__builtin_amdgcn_ds_bpermute((lane ^ o) << 2, __float_as_int(v))); }
; __device__ void gla3_item(const Params& p, int l, int item, LAS unsigned char* lds) {
;     ...
;         u32x2 w; w.x = cvt_pk_bf16(acc[0], acc[1]); w.y = cvt_pk_bf16(acc[2], acc[3]);
;         *(LAS u32x2*)(hl + GL_P + (wv * 16 + fr) * 144 + (st * 16 + 4 * fq) * 2) = w; }
;     __syncthreads();
;     bf16x8 pf[2];
; #pragma unroll
;     for (int ks = 0; ks < 2; ++ks) pf[ks] = *(const LAS bf16x8*)(hl + GL_P + (wv * 16 + fr) * 144 + (ks * 32 + fq * 8) * 2);
;     f32x4 o[8]; float ss = 0.f;
; #pragma unroll
;     for (int nt = 0; nt < 8; ++nt) { f32x4 acc = (f32x4){0.f, 0.f, 0.f, 0.f};
; #pragma unroll
;         for (int ks = 0; ks < 2; ++ks) { const bf16x8 cf = *(const LAS bf16x8*)(hl + GL_VT + (nt * 16 + fr) * 144 + (ks * 32 + fq * 8) * 2); acc = mfma16(cf, pf[ks], acc); }
;     ...
; #pragma unroll
;         for (int ks = 0; ks < 2; ++ks) acc = mfma16(spf[nt][ks], qf[ks], acc);
;     ...
;         o[nt] = acc; ss += acc[0] * acc[0] + acc[1] * acc[1] + acc[2] * acc[2] + acc[3] * acc[3]; }
;     ss += shx(ss, lane, 16); ss += shx(ss, lane, 32);
.LBB0_520:
	s_or_b64 exec, exec, s[10:11]
	v_cvt_pk_bf16_f32 v74, v75, v74
	v_cvt_pk_bf16_f32 v75, v78, v79
	ds_write_b64 v76, v[74:75] offset:18528
	s_waitcnt lgkmcnt(0)
	s_barrier
	ds_read_b128 v[78:81], v102 offset:18432
	ds_read_b128 v[74:77], v102 offset:18496
	ds_read_b128 v[102:105], v0 offset:27648
	ds_read_b128 v[106:109], v0 offset:27712
	s_waitcnt lgkmcnt(1)
	v_mfma_f32_16x16x32_bf16 v[102:105], v[102:105], v[78:81], 0
	s_waitcnt lgkmcnt(0)
	v_mfma_f32_16x16x32_bf16 v[102:105], v[106:109], v[74:77], v[102:105]
	v_mfma_f32_16x16x32_bf16 v[58:61], v[58:61], v[70:73], v[102:105]
	v_mfma_f32_16x16x32_bf16 v[58:61], v[62:65], v[66:69], v[58:61]
	ds_read_b128 v[62:65], v0 offset:29952
	s_nop 4
	ds_read_b128 v[102:105], v0 offset:30016
	s_waitcnt lgkmcnt(1)
	v_mfma_f32_16x16x32_bf16 v[62:65], v[62:65], v[78:81], 0
	v_mul_f32_e32 v106, v59, v59
	v_fmac_f32_e32 v106, v58, v58
	v_fmac_f32_e32 v106, v60, v60
	s_waitcnt lgkmcnt(0)
	v_mfma_f32_16x16x32_bf16 v[62:65], v[102:105], v[74:77], v[62:65]
	v_fmac_f32_e32 v106, v61, v61
	v_mfma_f32_16x16x32_bf16 v[50:53], v[50:53], v[70:73], v[62:65]
	v_mfma_f32_16x16x32_bf16 v[50:53], v[54:57], v[66:69], v[50:53]
	s_nop 4
	ds_read_b128 v[62:65], v0 offset:32320
	s_nop 1
	v_mul_f32_e32 v54, v51, v51
	v_fmac_f32_e32 v54, v50, v50
	v_fmac_f32_e32 v54, v52, v52
	v_fmac_f32_e32 v54, v53, v53
	v_add_f32_e32 v102, v106, v54
	ds_read_b128 v[54:57], v0 offset:32256
	s_waitcnt lgkmcnt(0)
	v_mfma_f32_16x16x32_bf16 v[54:57], v[54:57], v[78:81], 0
	v_mfma_f32_16x16x32_bf16 v[54:57], v[62:65], v[74:77], v[54:57]
	v_mfma_f32_16x16x32_bf16 v[46:49], v[46:49], v[70:73], v[54:57]
	v_mfma_f32_16x16x32_bf16 v[42:45], v[42:45], v[66:69], v[46:49]
	s_nop 5
	ds_read_b128 v[54:57], v0 offset:34624
	s_nop 0
	v_mul_f32_e32 v46, v43, v43
	v_fmac_f32_e32 v46, v42, v42
	v_fmac_f32_e32 v46, v44, v44
	v_fmac_f32_e32 v46, v45, v45
	v_add_f32_e32 v62, v102, v46
	ds_read_b128 v[46:49], v0 offset:34560
	s_waitcnt lgkmcnt(0)
	v_mfma_f32_16x16x32_bf16 v[46:49], v[46:49], v[78:81], 0
	v_mfma_f32_16x16x32_bf16 v[46:49], v[54:57], v[74:77], v[46:49]
	v_mfma_f32_16x16x32_bf16 v[34:37], v[34:37], v[70:73], v[46:49]
	v_mfma_f32_16x16x32_bf16 v[34:37], v[38:41], v[66:69], v[34:37]
	s_nop 5
	ds_read_b128 v[46:49], v0 offset:36928
	s_nop 0
	v_mul_f32_e32 v38, v35, v35
	v_fmac_f32_e32 v38, v34, v34
	v_fmac_f32_e32 v38, v36, v36
	v_fmac_f32_e32 v38, v37, v37
	v_add_f32_e32 v54, v62, v38
	ds_read_b128 v[38:41], v0 offset:36864
	s_waitcnt lgkmcnt(0)
	v_mfma_f32_16x16x32_bf16 v[38:41], v[38:41], v[78:81], 0
	v_mfma_f32_16x16x32_bf16 v[38:41], v[46:49], v[74:77], v[38:41]
	v_mfma_f32_16x16x32_bf16 v[26:29], v[26:29], v[70:73], v[38:41]
	v_mfma_f32_16x16x32_bf16 v[26:29], v[30:33], v[66:69], v[26:29]
	s_nop 5
	ds_read_b128 v[38:41], v0 offset:39232
	s_nop 0
	v_mul_f32_e32 v30, v27, v27
	v_fmac_f32_e32 v30, v26, v26
	v_fmac_f32_e32 v30, v28, v28
	v_fmac_f32_e32 v30, v29, v29
	v_add_f32_e32 v46, v54, v30
	ds_read_b128 v[30:33], v0 offset:39168
	s_waitcnt lgkmcnt(0)
	v_mfma_f32_16x16x32_bf16 v[30:33], v[30:33], v[78:81], 0
	v_mfma_f32_16x16x32_bf16 v[30:33], v[38:41], v[74:77], v[30:33]
	v_mfma_f32_16x16x32_bf16 v[18:21], v[18:21], v[70:73], v[30:33]
	v_mfma_f32_16x16x32_bf16 v[18:21], v[22:25], v[66:69], v[18:21]
	s_nop 5
	ds_read_b128 v[30:33], v0 offset:41536
	s_nop 0
	v_mul_f32_e32 v22, v19, v19
	v_fmac_f32_e32 v22, v18, v18
	v_fmac_f32_e32 v22, v20, v20
	v_fmac_f32_e32 v22, v21, v21
	v_add_f32_e32 v38, v46, v22
	ds_read_b128 v[22:25], v0 offset:41472
	s_waitcnt lgkmcnt(0)
	v_mfma_f32_16x16x32_bf16 v[22:25], v[22:25], v[78:81], 0
	v_mfma_f32_16x16x32_bf16 v[22:25], v[30:33], v[74:77], v[22:25]
	v_mfma_f32_16x16x32_bf16 v[10:13], v[10:13], v[70:73], v[22:25]
	v_mfma_f32_16x16x32_bf16 v[10:13], v[14:17], v[66:69], v[10:13]
	s_nop 5
	ds_read_b128 v[22:25], v0 offset:43840
	s_nop 0
	v_mul_f32_e32 v14, v11, v11
	v_fmac_f32_e32 v14, v10, v10
	v_fmac_f32_e32 v14, v12, v12
	v_fmac_f32_e32 v14, v13, v13
	v_add_f32_e32 v30, v38, v14
	ds_read_b128 v[14:17], v0 offset:43776
	s_waitcnt lgkmcnt(0)
	v_mfma_f32_16x16x32_bf16 v[14:17], v[14:17], v[78:81], 0
	v_mfma_f32_16x16x32_bf16 v[14:17], v[22:25], v[74:77], v[14:17]
	v_mfma_f32_16x16x32_bf16 v[6:9], v[6:9], v[70:73], v[14:17]
	v_mfma_f32_16x16x32_bf16 v[2:5], v[2:5], v[66:69], v[6:9]
	s_nop 6
	v_xor_b32_e32 v6, 64, v100
	v_mul_f32_e32 v0, v3, v3
	v_fmac_f32_e32 v0, v2, v2
	v_fmac_f32_e32 v0, v4, v4
	v_fmac_f32_e32 v0, v5, v5
	v_add_f32_e32 v0, v30, v0
	ds_bpermute_b32 v6, v6, v0
	s_waitcnt lgkmcnt(0)
	v_add_f32_e32 v0, v0, v6
	v_xor_b32_e32 v6, 0x80, v100
	ds_bpermute_b32 v6, v6, v0
	s_and_saveexec_b64 s[10:11], vcc
	s_cbranch_execz .LBB0_522
; __device__ __forceinline__ float bflo(unsigned w) { return __uint_as_float(w << 16); }
; __device__ __forceinline__ float bfhi(unsigned w) { return __uint_as_float(w & 0xffff0000u); }
; __device__ __forceinline__ unsigned cvt_pk_bf16(float lo, float hi) { const f32x2 f = {lo, hi}; const bf16n2 v = __builtin_convertvector(f, bf16n2); return __builtin_bit_cast(unsigned, v); }
; __device__ __forceinline__ float siluf_(float x) { return x * sigmoidf_(x); }
; __device__ void gla3_item(const Params& p, int l, int item, LAS unsigned char* lds) {
;     ...
;     const float rstd = rsqrtf(ss * (1.0f / 128.0f) + EPS);
;     if (rb < TB) { const float* gn = p.gla_norm + (size_t)l * 512 + h * 128;
; #pragma unroll
;         for (int nt = 0; nt < 8; ++nt) { const int dv = nt * 16 + 4 * fq; const f32x4 gv = *(const f32x4*)(gn + dv); const u32x2 rw = rwv[nt];
;             const float v0 = o[nt][0] * rstd * gv[0] * siluf_(bflo(rw.x)), v1 = o[nt][1] * rstd * gv[1] * siluf_(bfhi(rw.x)),
;                         v2 = o[nt][2] * rstd * gv[2] * siluf_(bflo(rw.y)), v3 = o[nt][3] * rstd * gv[3] * siluf_(bfhi(rw.y));
;             u32x2 w; w.x = cvt_pk_bf16(v0, v1); w.y = cvt_pk_bf16(v2, v3); if (!p.dry) *(u32x2*)(rowp + C_V + h * 128 + dv) = w; } }
	s_waitcnt lgkmcnt(0)
	v_add_f32_e32 v0, v0, v6
	v_fmamk_f32 v0, v0, 0x3c000000, v229
	s_mov_b32 s15, 0x800000
	v_cmp_gt_f32_e32 vcc, s15, v0
	v_mul_f32_e32 v6, 0x4b800000, v0
	s_lshl_b32 s14, s14, 2
	v_cndmask_b32_e32 v0, v0, v6, vcc
	v_rsq_f32_e32 v0, v0
	s_add_u32 s40, s19, s14
	s_addc_u32 s41, s72, 0
	v_lshlrev_b32_e32 v8, 16, v98
	v_mul_f32_e32 v6, 0x45800000, v0
	v_cndmask_b32_e32 v0, v0, v6, vcc
	v_lshlrev_b32_e32 v6, 2, v101
	v_bfe_u32 v202, v228, 4, 1
	v_mul_u32_u24_e32 v202, 24, v202
	v_mov_b32_e32 v203, 0
	v_lshl_add_u64 v[82:83], v[82:83], 0, v[202:203]
	global_load_dwordx4 v[204:207], v6, s[40:41]
	global_load_dwordx4 v[208:211], v6, s[40:41] offset:64
	global_load_dwordx4 v[212:215], v6, s[40:41] offset:128
	global_load_dwordx4 v[216:219], v6, s[40:41] offset:192
	global_load_dwordx4 v[220:223], v6, s[40:41] offset:256
	global_load_dwordx4 v[224:227], v6, s[40:41] offset:320
	global_load_dwordx4 v[240:243], v6, s[40:41] offset:384
	global_load_dwordx4 v[244:247], v6, s[40:41] offset:448
	v_mul_f32_e32 v7, 0xbfb8aa3b, v8
	v_exp_f32_e32 v7, v7
	v_and_b32_e32 v9, 0xffff0000, v98
	v_pk_mul_f32 v[24:25], v[58:59], v[0:1] op_sel_hi:[1,0]
	v_pk_mul_f32 v[18:19], v[18:19], v[0:1] op_sel_hi:[1,0]
	v_add_f32_e32 v7, 1.0, v7
	v_rcp_f32_e32 v22, v7
	v_mul_f32_e32 v7, 0xbfb8aa3b, v9
	v_exp_f32_e32 v7, v7
	v_pk_mul_f32 v[20:21], v[20:21], v[0:1] op_sel_hi:[1,0]
	v_pk_mul_f32 v[10:11], v[10:11], v[0:1] op_sel_hi:[1,0]
	v_pk_mul_f32 v[12:13], v[12:13], v[0:1] op_sel_hi:[1,0]
	v_add_f32_e32 v7, 1.0, v7
	v_rcp_f32_e32 v23, v7
	v_pk_mul_f32 v[2:3], v[2:3], v[0:1] op_sel_hi:[1,0]
	v_pk_mul_f32 v[4:5], v[4:5], v[0:1] op_sel_hi:[1,0]
	v_pk_mul_f32 v[8:9], v[22:23], v[8:9]
	s_waitcnt vmcnt(0)
	v_pk_mul_f32 v[14:15], v[24:25], v[204:205]
	s_nop 0
	v_pk_mul_f32 v[8:9], v[8:9], v[14:15]
	v_lshlrev_b32_e32 v14, 16, v99
	v_mul_f32_e32 v7, 0xbfb8aa3b, v14
	v_exp_f32_e32 v7, v7
	v_and_b32_e32 v15, 0xffff0000, v99
	v_pk_mul_f32 v[24:25], v[60:61], v[0:1] op_sel_hi:[1,0]
	v_cvt_pk_bf16_f32 v248, v8, v9
	v_add_f32_e32 v7, 1.0, v7
	v_rcp_f32_e32 v22, v7
	v_mul_f32_e32 v7, 0xbfb8aa3b, v15
	v_exp_f32_e32 v7, v7
	v_pk_mul_f32 v[16:17], v[24:25], v[206:207]
	v_pk_mul_f32 v[24:25], v[50:51], v[0:1] op_sel_hi:[1,0]
	v_add_f32_e32 v7, 1.0, v7
	v_rcp_f32_e32 v23, v7
	s_nop 0
	v_pk_mul_f32 v[14:15], v[22:23], v[14:15]
	s_nop 0
	v_pk_mul_f32 v[14:15], v[14:15], v[16:17]
	s_nop 0
	v_cvt_pk_bf16_f32 v249, v14, v15
	v_lshlrev_b32_e32 v8, 16, v96
	v_mul_f32_e32 v7, 0xbfb8aa3b, v8
	v_exp_f32_e32 v7, v7
	v_and_b32_e32 v9, 0xffff0000, v96
	v_add_f32_e32 v7, 1.0, v7
	v_rcp_f32_e32 v22, v7
	v_mul_f32_e32 v7, 0xbfb8aa3b, v9
	v_exp_f32_e32 v7, v7
	v_pk_mul_f32 v[14:15], v[24:25], v[208:209]
	v_add_f32_e32 v7, 1.0, v7
	v_rcp_f32_e32 v23, v7
	v_pk_mul_f32 v[24:25], v[52:53], v[0:1] op_sel_hi:[1,0]
	v_pk_mul_f32 v[8:9], v[22:23], v[8:9]
	s_nop 0
	v_pk_mul_f32 v[8:9], v[8:9], v[14:15]
	v_lshlrev_b32_e32 v14, 16, v97
	v_mul_f32_e32 v7, 0xbfb8aa3b, v14
	v_exp_f32_e32 v7, v7
	v_and_b32_e32 v15, 0xffff0000, v97
	v_pk_mul_f32 v[16:17], v[24:25], v[210:211]
	v_cvt_pk_bf16_f32 v250, v8, v9
	v_add_f32_e32 v7, 1.0, v7
	v_rcp_f32_e32 v22, v7
	v_mul_f32_e32 v7, 0xbfb8aa3b, v15
	v_exp_f32_e32 v7, v7
	v_pk_mul_f32 v[24:25], v[42:43], v[0:1] op_sel_hi:[1,0]
	v_add_f32_e32 v7, 1.0, v7
	v_rcp_f32_e32 v23, v7
	s_nop 0
	v_pk_mul_f32 v[14:15], v[22:23], v[14:15]
	s_nop 0
	v_pk_mul_f32 v[14:15], v[14:15], v[16:17]
	s_nop 0
	v_cvt_pk_bf16_f32 v251, v14, v15
	s_nop 1
	v_permlane16_swap_b32 v248, v250
	v_permlane16_swap_b32 v249, v251
	global_store_dwordx4 v[82:83], v[248:251], off offset:2048
	v_lshlrev_b32_e32 v8, 16, v94
	v_mul_f32_e32 v7, 0xbfb8aa3b, v8
	v_exp_f32_e32 v7, v7
	v_and_b32_e32 v9, 0xffff0000, v94
	v_add_f32_e32 v7, 1.0, v7
	v_rcp_f32_e32 v22, v7
	v_mul_f32_e32 v7, 0xbfb8aa3b, v9
	v_exp_f32_e32 v7, v7
	v_pk_mul_f32 v[14:15], v[24:25], v[212:213]
	v_add_f32_e32 v7, 1.0, v7
	v_rcp_f32_e32 v23, v7
	v_pk_mul_f32 v[24:25], v[44:45], v[0:1] op_sel_hi:[1,0]
	v_pk_mul_f32 v[8:9], v[22:23], v[8:9]
	s_nop 0
	v_pk_mul_f32 v[8:9], v[8:9], v[14:15]
	v_lshlrev_b32_e32 v14, 16, v95
	v_mul_f32_e32 v7, 0xbfb8aa3b, v14
	v_exp_f32_e32 v7, v7
	v_and_b32_e32 v15, 0xffff0000, v95
	v_pk_mul_f32 v[16:17], v[24:25], v[214:215]
	v_cvt_pk_bf16_f32 v248, v8, v9
	v_add_f32_e32 v7, 1.0, v7
	v_rcp_f32_e32 v22, v7
	v_mul_f32_e32 v7, 0xbfb8aa3b, v15
	v_exp_f32_e32 v7, v7
	v_pk_mul_f32 v[24:25], v[34:35], v[0:1] op_sel_hi:[1,0]
	v_add_f32_e32 v7, 1.0, v7
	v_rcp_f32_e32 v23, v7
	s_nop 0
	v_pk_mul_f32 v[14:15], v[22:23], v[14:15]
	s_nop 0
	v_pk_mul_f32 v[14:15], v[14:15], v[16:17]
	s_nop 0
	v_cvt_pk_bf16_f32 v249, v14, v15
	v_lshlrev_b32_e32 v8, 16, v92
	v_mul_f32_e32 v7, 0xbfb8aa3b, v8
	v_exp_f32_e32 v7, v7
	v_and_b32_e32 v9, 0xffff0000, v92
	v_add_f32_e32 v7, 1.0, v7
	v_rcp_f32_e32 v22, v7
	v_mul_f32_e32 v7, 0xbfb8aa3b, v9
	v_exp_f32_e32 v7, v7
	v_pk_mul_f32 v[14:15], v[24:25], v[216:217]
; __device__ __forceinline__ float bflo(unsigned w) { return __uint_as_float(w << 16); }
; __device__ __forceinline__ float bfhi(unsigned w) { return __uint_as_float(w & 0xffff0000u); }
; __device__ __forceinline__ unsigned cvt_pk_bf16(float lo, float hi) { const f32x2 f = {lo, hi}; const bf16n2 v = __builtin_convertvector(f, bf16n2); return __builtin_bit_cast(unsigned, v); }
; __device__ __forceinline__ float siluf_(float x) { return x * sigmoidf_(x); }
; __device__ void gla3_item(const Params& p, int l, int item, LAS unsigned char* lds) {
;     ...
;     const float rstd = rsqrtf(ss * (1.0f / 128.0f) + EPS);
;     if (rb < TB) { const float* gn = p.gla_norm + (size_t)l * 512 + h * 128;
; #pragma unroll
;         for (int nt = 0; nt < 8; ++nt) { const int dv = nt * 16 + 4 * fq; const f32x4 gv = *(const f32x4*)(gn + dv); const u32x2 rw = rwv[nt];
;             const float v0 = o[nt][0] * rstd * gv[0] * siluf_(bflo(rw.x)), v1 = o[nt][1] * rstd * gv[1] * siluf_(bfhi(rw.x)),
;                         v2 = o[nt][2] * rstd * gv[2] * siluf_(bflo(rw.y)), v3 = o[nt][3] * rstd * gv[3] * siluf_(bfhi(rw.y));
;             u32x2 w; w.x = cvt_pk_bf16(v0, v1); w.y = cvt_pk_bf16(v2, v3); if (!p.dry) *(u32x2*)(rowp + C_V + h * 128 + dv) = w; } }
	v_add_f32_e32 v7, 1.0, v7
	v_rcp_f32_e32 v23, v7
	v_pk_mul_f32 v[24:25], v[36:37], v[0:1] op_sel_hi:[1,0]
	v_pk_mul_f32 v[8:9], v[22:23], v[8:9]
	s_nop 0
	v_pk_mul_f32 v[8:9], v[8:9], v[14:15]
	v_lshlrev_b32_e32 v14, 16, v93
	v_mul_f32_e32 v7, 0xbfb8aa3b, v14
	v_exp_f32_e32 v7, v7
	v_and_b32_e32 v15, 0xffff0000, v93
	v_pk_mul_f32 v[16:17], v[24:25], v[218:219]
	v_cvt_pk_bf16_f32 v250, v8, v9
	v_add_f32_e32 v7, 1.0, v7
	v_rcp_f32_e32 v22, v7
	v_mul_f32_e32 v7, 0xbfb8aa3b, v15
	v_exp_f32_e32 v7, v7
	v_pk_mul_f32 v[24:25], v[26:27], v[0:1] op_sel_hi:[1,0]
	v_add_f32_e32 v7, 1.0, v7
	v_rcp_f32_e32 v23, v7
	s_nop 0
	v_pk_mul_f32 v[14:15], v[22:23], v[14:15]
	s_nop 0
	v_pk_mul_f32 v[14:15], v[14:15], v[16:17]
	s_nop 0
	v_cvt_pk_bf16_f32 v251, v14, v15
	s_nop 1
	v_permlane16_swap_b32 v248, v250
	v_permlane16_swap_b32 v249, v251
	global_store_dwordx4 v[82:83], v[248:251], off offset:2112
	v_lshlrev_b32_e32 v8, 16, v90
	v_mul_f32_e32 v7, 0xbfb8aa3b, v8
	v_exp_f32_e32 v7, v7
	v_and_b32_e32 v9, 0xffff0000, v90
	v_add_f32_e32 v7, 1.0, v7
	v_rcp_f32_e32 v22, v7
	v_mul_f32_e32 v7, 0xbfb8aa3b, v9
	v_exp_f32_e32 v7, v7
	v_pk_mul_f32 v[14:15], v[24:25], v[220:221]
	v_add_f32_e32 v7, 1.0, v7
	v_rcp_f32_e32 v23, v7
	v_pk_mul_f32 v[24:25], v[28:29], v[0:1] op_sel_hi:[1,0]
	v_pk_mul_f32 v[8:9], v[22:23], v[8:9]
	s_nop 0
	v_pk_mul_f32 v[8:9], v[8:9], v[14:15]
	v_lshlrev_b32_e32 v14, 16, v91
	v_mul_f32_e32 v7, 0xbfb8aa3b, v14
	v_exp_f32_e32 v7, v7
	v_and_b32_e32 v15, 0xffff0000, v91
	v_pk_mul_f32 v[16:17], v[24:25], v[222:223]
	v_cvt_pk_bf16_f32 v248, v8, v9
	v_add_f32_e32 v7, 1.0, v7
	v_rcp_f32_e32 v22, v7
	v_mul_f32_e32 v7, 0xbfb8aa3b, v15
	v_exp_f32_e32 v7, v7
	s_nop 0
	v_add_f32_e32 v7, 1.0, v7
	v_rcp_f32_e32 v23, v7
	s_nop 0
	v_pk_mul_f32 v[14:15], v[22:23], v[14:15]
	s_nop 0
	v_pk_mul_f32 v[14:15], v[14:15], v[16:17]
	s_nop 0
	v_cvt_pk_bf16_f32 v249, v14, v15
	v_lshlrev_b32_e32 v8, 16, v88
	v_mul_f32_e32 v7, 0xbfb8aa3b, v8
	v_exp_f32_e32 v7, v7
	v_and_b32_e32 v9, 0xffff0000, v88
	v_add_f32_e32 v7, 1.0, v7
	v_rcp_f32_e32 v22, v7
	v_mul_f32_e32 v7, 0xbfb8aa3b, v9
	v_exp_f32_e32 v7, v7
	v_pk_mul_f32 v[14:15], v[18:19], v[224:225]
	v_add_f32_e32 v7, 1.0, v7
	v_rcp_f32_e32 v23, v7
	v_pk_mul_f32 v[16:17], v[20:21], v[226:227]
	v_pk_mul_f32 v[8:9], v[22:23], v[8:9]
	s_nop 0
	v_pk_mul_f32 v[8:9], v[8:9], v[14:15]
	v_lshlrev_b32_e32 v14, 16, v89
	v_mul_f32_e32 v7, 0xbfb8aa3b, v14
	v_exp_f32_e32 v7, v7
	v_and_b32_e32 v15, 0xffff0000, v89
	v_cvt_pk_bf16_f32 v250, v8, v9
	v_add_f32_e32 v7, 1.0, v7
	v_rcp_f32_e32 v18, v7
	v_mul_f32_e32 v7, 0xbfb8aa3b, v15
	v_exp_f32_e32 v7, v7
	s_nop 0
	v_add_f32_e32 v7, 1.0, v7
	v_rcp_f32_e32 v19, v7
	s_nop 0
	v_pk_mul_f32 v[14:15], v[18:19], v[14:15]
	s_nop 0
	v_pk_mul_f32 v[14:15], v[14:15], v[16:17]
	s_nop 0
	v_cvt_pk_bf16_f32 v251, v14, v15
	s_nop 1
	v_permlane16_swap_b32 v248, v250
	v_permlane16_swap_b32 v249, v251
	global_store_dwordx4 v[82:83], v[248:251], off offset:2176
	v_lshlrev_b32_e32 v8, 16, v86
	v_mul_f32_e32 v7, 0xbfb8aa3b, v8
	v_exp_f32_e32 v7, v7
	v_and_b32_e32 v9, 0xffff0000, v86
	v_add_f32_e32 v7, 1.0, v7
	v_rcp_f32_e32 v18, v7
	v_mul_f32_e32 v7, 0xbfb8aa3b, v9
	v_exp_f32_e32 v7, v7
	v_pk_mul_f32 v[10:11], v[10:11], v[240:241]
	v_add_f32_e32 v7, 1.0, v7
	v_rcp_f32_e32 v19, v7
	v_pk_mul_f32 v[12:13], v[12:13], v[242:243]
	v_pk_mul_f32 v[8:9], v[18:19], v[8:9]
	s_nop 0
	v_pk_mul_f32 v[8:9], v[8:9], v[10:11]
	v_lshlrev_b32_e32 v10, 16, v87
	v_mul_f32_e32 v7, 0xbfb8aa3b, v10
	v_exp_f32_e32 v7, v7
	v_and_b32_e32 v11, 0xffff0000, v87
	v_cvt_pk_bf16_f32 v248, v8, v9
	v_add_f32_e32 v7, 1.0, v7
	v_rcp_f32_e32 v14, v7
	v_mul_f32_e32 v7, 0xbfb8aa3b, v11
	v_exp_f32_e32 v7, v7
	s_nop 0
	v_add_f32_e32 v7, 1.0, v7
	v_rcp_f32_e32 v15, v7
	s_nop 0
	v_pk_mul_f32 v[10:11], v[14:15], v[10:11]
	s_nop 0
	v_pk_mul_f32 v[10:11], v[10:11], v[12:13]
	s_nop 0
	v_cvt_pk_bf16_f32 v249, v10, v11
	v_lshlrev_b32_e32 v10, 16, v84
	v_and_b32_e32 v11, 0xffff0000, v84
	v_mul_f32_e32 v12, 0xbfb8aa3b, v10
	v_exp_f32_e32 v12, v12
	v_pk_mul_f32 v[2:3], v[2:3], v[244:245]
	v_mul_f32_e32 v6, 0xbfb8aa3b, v11
	v_exp_f32_e32 v6, v6
	v_add_f32_e32 v12, 1.0, v12
	v_rcp_f32_e32 v12, v12
	v_pk_mul_f32 v[4:5], v[4:5], v[246:247]
	v_add_f32_e32 v6, 1.0, v6
	v_rcp_f32_e32 v13, v6
	s_nop 0
	v_pk_mul_f32 v[6:7], v[12:13], v[10:11]
	s_nop 0
	v_pk_mul_f32 v[2:3], v[6:7], v[2:3]
	v_lshlrev_b32_e32 v6, 16, v85
	v_and_b32_e32 v7, 0xffff0000, v85
	v_cvt_pk_bf16_f32 v250, v2, v3
	v_mul_f32_e32 v3, 0xbfb8aa3b, v6
	v_mul_f32_e32 v0, 0xbfb8aa3b, v7
	v_exp_f32_e32 v3, v3
	v_exp_f32_e32 v0, v0
	v_add_f32_e32 v3, 1.0, v3
	v_add_f32_e32 v0, 1.0, v0
	v_rcp_f32_e32 v10, v3
	v_rcp_f32_e32 v11, v0
	s_nop 0
	v_pk_mul_f32 v[6:7], v[10:11], v[6:7]
	s_nop 0
	v_pk_mul_f32 v[4:5], v[6:7], v[4:5]
	s_nop 0
	v_cvt_pk_bf16_f32 v251, v4, v5
	s_nop 1
	v_permlane16_swap_b32 v248, v250
	v_permlane16_swap_b32 v249, v251
	global_store_dwordx4 v[82:83], v[248:251], off offset:2240

; #define LAS __attribute__((address_space(3)))
; __device__ __forceinline__ unsigned cvt_pk_bf16(float lo, float hi) { const f32x2 f = {lo, hi}; const bf16n2 v = __builtin_convertvector(f, bf16n2); return __builtin_bit_cast(unsigned, v); }
; __device__ __forceinline__ f32x4 mfma16(bf16x8 colfrag, bf16x8 rowfrag, f32x4 acc) { return __builtin_amdgcn_mfma_f32_16x16x32_bf16(colfrag, rowfrag, acc, 0, 0, 0); }
; __device__ void gla1_item(const Params& p, int l, int item, LAS unsigned char* lds) {
;     ...
;     bf16_t* kvT = (bf16_t*)((unsigned char*)p.out + OS_KVT) + ((size_t)bh * GCH + n) * 8192;
; #pragma unroll
;     for (int mt = 0; mt < 2; ++mt) { const int dv0 = wv * 32 + mt * 16;
;         bf16x8 rf[2];
; #pragma unroll
;         for (int ks = 0; ks < 2; ++ks) rf[ks] = *(const LAS bf16x8*)(hl + GL_VT + (dv0 + fr) * 144 + (ks * 32 + fq * 8) * 2);
; #pragma unroll
;         for (int nt = 0; nt < 4; ++nt) { f32x4 acc = (f32x4){0.f, 0.f, 0.f, 0.f};
; #pragma unroll
;             for (int ks = 0; ks < 2; ++ks) { const bf16x8 cf = *(const LAS bf16x8*)(hl + GL_KI + (nt * 16 + fr) * 144 + (ks * 32 + fq * 8) * 2); acc = mfma16(cf, rf[ks], acc); }
;             u32x2 w; w.x = cvt_pk_bf16(acc[0], acc[1]); w.y = cvt_pk_bf16(acc[2], acc[3]);
;             *(u32x2*)(kvT + (dv0 + fr) * 64 + nt * 16 + 4 * fq) = w; } }
.LBB0_594:
	s_or_b64 exec, exec, s[22:23]
	v_bfe_u32 v0, v8, 4, 2
	v_lshlrev_b64 v[2:3], 14, v[6:7]
	v_and_b32_e32 v10, 15, v8
	v_lshl_add_u64 v[2:3], s[14:15], 0, v[2:3]
	v_lshrrev_b32_e32 v4, 1, v8
	v_lshl_add_u32 v11, v0, 4, v15
	v_lshlrev_b32_e32 v0, 3, v0
	s_movk_i32 s22, 0x60
	v_lshl_add_u64 v[42:43], v[2:3], 0, v[0:1]
	v_bfe_u32 v104, v8, 4, 1
	v_mul_u32_u24_e32 v104, 24, v104
	v_mov_b32_e32 v105, 0
	v_lshl_add_u64 v[42:43], v[42:43], 0, v[104:105]
	v_and_or_b32 v0, v4, s22, v10
	v_mad_u32_u24 v46, v0, s1, v11
	v_mad_u32_u24 v38, v10, s1, v11
	s_waitcnt lgkmcnt(0)
	s_barrier
	ds_read_b128 v[2:5], v46 offset:27648
	ds_read_b128 v[6:9], v46 offset:27712
	ds_read_b128 v[10:13], v38 offset:9216
	ds_read_b128 v[18:21], v38 offset:9280
	s_waitcnt lgkmcnt(1)
	v_mfma_f32_16x16x32_bf16 v[14:17], v[10:13], v[2:5], 0
	v_lshlrev_b32_e32 v0, 7, v0
	v_lshl_add_u64 v[44:45], v[42:43], 0, v[0:1]
	ds_read_b128 v[26:29], v38 offset:11584
	s_waitcnt lgkmcnt(1)
	v_mfma_f32_16x16x32_bf16 v[14:17], v[18:21], v[6:9], v[14:17]
	v_or_b32_e32 v0, 0x800, v0
	v_lshl_add_u64 v[42:43], v[42:43], 0, v[0:1]
	ds_read_b128 v[34:37], v38 offset:13888
	s_nop 4
	v_cvt_pk_bf16_f32 v96, v14, v15
	v_cvt_pk_bf16_f32 v97, v16, v17
	ds_read_b128 v[14:17], v38 offset:11520
	s_waitcnt lgkmcnt(0)
	v_mfma_f32_16x16x32_bf16 v[22:25], v[14:17], v[2:5], 0
	v_mfma_f32_16x16x32_bf16 v[22:25], v[26:29], v[6:9], v[22:25]
	s_nop 7
	v_cvt_pk_bf16_f32 v98, v22, v23
	v_cvt_pk_bf16_f32 v99, v24, v25
	s_nop 1
	v_permlane16_swap_b32 v96, v98
	v_permlane16_swap_b32 v97, v99
	global_store_dwordx4 v[44:45], v[96:99], off
	ds_read_b128 v[22:25], v38 offset:13824
	s_waitcnt lgkmcnt(0)
	v_mfma_f32_16x16x32_bf16 v[30:33], v[22:25], v[2:5], 0
	v_mfma_f32_16x16x32_bf16 v[30:33], v[34:37], v[6:9], v[30:33]
	s_nop 7
	v_cvt_pk_bf16_f32 v100, v30, v31
	v_cvt_pk_bf16_f32 v101, v32, v33
	ds_read_b128 v[30:33], v38 offset:16128
	ds_read_b128 v[38:41], v38 offset:16192
	s_waitcnt lgkmcnt(1)
	v_mfma_f32_16x16x32_bf16 v[2:5], v[30:33], v[2:5], 0
	s_waitcnt lgkmcnt(0)
	v_mfma_f32_16x16x32_bf16 v[2:5], v[38:41], v[6:9], v[2:5]
	s_nop 7
	v_cvt_pk_bf16_f32 v102, v2, v3
	v_cvt_pk_bf16_f32 v103, v4, v5
	s_nop 1
	v_permlane16_swap_b32 v100, v102
	v_permlane16_swap_b32 v101, v103
	global_store_dwordx4 v[44:45], v[100:103], off offset:64
	ds_read_b128 v[2:5], v46 offset:29952
	ds_read_b128 v[6:9], v46 offset:30016
	s_waitcnt lgkmcnt(1)
	v_mfma_f32_16x16x32_bf16 v[10:13], v[10:13], v[2:5], 0
	s_waitcnt lgkmcnt(0)
	v_mfma_f32_16x16x32_bf16 v[10:13], v[18:21], v[6:9], v[10:13]
	s_nop 7
	v_cvt_pk_bf16_f32 v96, v10, v11
	v_cvt_pk_bf16_f32 v97, v12, v13
	v_mfma_f32_16x16x32_bf16 v[10:13], v[14:17], v[2:5], 0
	v_mfma_f32_16x16x32_bf16 v[10:13], v[26:29], v[6:9], v[10:13]
	s_nop 7
	v_cvt_pk_bf16_f32 v98, v10, v11
	v_cvt_pk_bf16_f32 v99, v12, v13
	s_nop 1
	v_permlane16_swap_b32 v96, v98
	v_permlane16_swap_b32 v97, v99
	global_store_dwordx4 v[42:43], v[96:99], off
	v_mfma_f32_16x16x32_bf16 v[10:13], v[22:25], v[2:5], 0
	v_mfma_f32_16x16x32_bf16 v[2:5], v[30:33], v[2:5], 0
	v_mfma_f32_16x16x32_bf16 v[10:13], v[34:37], v[6:9], v[10:13]
	v_mfma_f32_16x16x32_bf16 v[2:5], v[38:41], v[6:9], v[2:5]
	s_nop 6
	v_cvt_pk_bf16_f32 v100, v10, v11
	v_cvt_pk_bf16_f32 v101, v12, v13
	v_cvt_pk_bf16_f32 v102, v2, v3
	v_cvt_pk_bf16_f32 v103, v4, v5
	s_nop 1
	v_permlane16_swap_b32 v100, v102
	v_permlane16_swap_b32 v101, v103
	global_store_dwordx4 v[42:43], v[100:103], off offset:64
	s_branch .LBB0_556
